# attnA passes 0-1: the wave's two query tiles share one K/V tile stream (6 tiles instead of 10, fragments read once, double-buffered); softmax without running max, guarded by a fallback to the running-
# speedup vs baseline: 1.0117x; 1.0117x over previous
; __device__ __forceinline__ void attnA_unit(const Args& a, int unit, LAS unsigned char* lds) {
;     ...
;         for (int e = 0; e < 2; ++e) {
;             const int qt = 2 * wid + e, r = qt % dl, i0 = (512 * blk) / dl + 32 * (qt / dl);
;             const int tq = dl * (i0 + ql) + r;
;             bf16x8 qf[4];
;             { const bf16_t* qp = P + ((size_t)b * SEQ + tq) * PW + 64 * hh + 8 * h;
; #pragma unroll
;               for (int s = 0; s < 4; ++s) qf[s] = *(const bf16x8*)(qp + 16 * s); }
;             f32x16 o0, o1;
; #pragma unroll
;             for (int i = 0; i < 16; ++i) { o0[i] = 0.f; o1[i] = 0.f; }
;             float m = -1e30f, l = 0.f;
;             int kt0 = 0, kt1 = 4;
;             if (i0 - 64 < 0) kt0 = (i0 - 32 < 0) ? 2 : 1;
;             if (i0 + 64 >= Ls) kt1 = (i0 + 32 >= Ls) ? 2 : 3;
;             const unsigned pitch = (unsigned)dl * (PW * 2);
;             u32x4 pk[4], pv[4];
;             { const size_t ro = (size_t)(dl * (i0 - 64 + 32 * kt0) + r) * (PW * 2); gload32(pk, kbase + ro, pitch, lane); gload32(pv, vbase + ro, pitch, lane); }
.LaT_pass:
	s_cmp_eq_u32 s82, 2
	s_cbranch_scc1 .LaT_sep
	s_lshr_b32 s0, s83, 1
	s_and_b32 s1, s0, 3
	s_lshr_b32 s0, s0, 2
	s_lshl_b32 s0, s0, 3
	s_or_b32 s0, s0, s1
	s_or_b32 s0, s0, 0
	s_or_b32 s1, s83, 0
	s_cmp_eq_u32 s82, 1
	s_cselect_b32 s0, s0, s1
	s_add_i32 s1, s72, -1
	s_and_b32 s74, s0, s1
	s_lshr_b32 s0, s0, s73
	s_lshl_b32 s0, s0, 5
	s_add_i32 s0, s0, s96
	v_add_u32_e32 v122, s0, v124
	v_lshlrev_b32_e32 v122, s73, v122
	v_add_u32_e32 v122, s74, v122
	v_add_u32_e32 v122, s76, v122
	v_mov_b32_e32 v123, 0
	v_add_u32_e32 v142, s0, v125
	v_lshlrev_b32_e32 v142, s73, v142
	v_add_u32_e32 v142, s74, v142
	v_add_u32_e32 v142, s76, v142
	s_movk_i32 s1, 0x1400
	v_mad_u64_u32 v[156:157], s[98:99], v122, s1, v[112:113]
	global_load_dwordx4 v[48:51], v[156:157], off
	global_load_dwordx4 v[52:55], v[156:157], off offset:32
	global_load_dwordx4 v[56:59], v[156:157], off offset:64
	global_load_dwordx4 v[60:63], v[156:157], off offset:96
	s_cmp_lt_i32 s0, 32
	s_cselect_b32 s1, 2, 1
	s_cmp_lt_i32 s0, 64
	s_cselect_b32 s86, s1, 0
	s_cmp_lt_i32 s0, s33
	s_cselect_b32 s1, 3, 2
	s_cmp_ge_i32 s0, s97
	s_cselect_b32 s87, s1, 4
	s_lshl_b32 s1, s86, 5
	s_add_i32 s0, s0, s1
	s_sub_i32 s75, s0, 64
	v_mov_b32_e32 v137, 0x0
	v_mov_b32_e32 v135, 0
	v_mov_b32_e32 v16, 0
	v_mov_b32_e32 v17, 0
	v_mov_b32_e32 v18, 0
	v_mov_b32_e32 v19, 0
	v_mov_b32_e32 v20, 0
	v_mov_b32_e32 v21, 0
	v_mov_b32_e32 v22, 0
	v_mov_b32_e32 v23, 0
	v_mov_b32_e32 v24, 0
	v_mov_b32_e32 v25, 0
	v_mov_b32_e32 v26, 0
	v_mov_b32_e32 v27, 0
	v_mov_b32_e32 v28, 0
	v_mov_b32_e32 v29, 0
	v_mov_b32_e32 v30, 0
	v_mov_b32_e32 v31, 0
	v_mov_b32_e32 v0, 0
	v_mov_b32_e32 v1, 0
	v_mov_b32_e32 v2, 0
	v_mov_b32_e32 v3, 0
	v_mov_b32_e32 v4, 0
	v_mov_b32_e32 v5, 0
	v_mov_b32_e32 v6, 0
	v_mov_b32_e32 v7, 0
	v_mov_b32_e32 v8, 0
	v_mov_b32_e32 v9, 0
	v_mov_b32_e32 v10, 0
	v_mov_b32_e32 v11, 0
	v_mov_b32_e32 v12, 0
	v_mov_b32_e32 v13, 0
	v_mov_b32_e32 v14, 0
	v_mov_b32_e32 v15, 0
	s_lshr_b32 s0, s83, 1
	s_and_b32 s1, s0, 3
	s_lshr_b32 s0, s0, 2
	s_lshl_b32 s0, s0, 3
	s_or_b32 s0, s0, s1
	s_or_b32 s0, s0, 4
	s_or_b32 s1, s83, 1
	s_cmp_eq_u32 s82, 1
	s_cselect_b32 s0, s0, s1
	s_add_i32 s1, s72, -1
	s_and_b32 s81, s0, s1
	s_lshr_b32 s0, s0, s73
	s_lshl_b32 s0, s0, 5
	s_add_i32 s0, s0, s96
	v_add_u32_e32 v216, s0, v124
	v_lshlrev_b32_e32 v216, s73, v216
	v_add_u32_e32 v216, s81, v216
	v_add_u32_e32 v216, s76, v216
	v_mov_b32_e32 v217, 0
	v_add_u32_e32 v224, s0, v125
	v_lshlrev_b32_e32 v224, s73, v224
	v_add_u32_e32 v224, s81, v224
	v_add_u32_e32 v224, s76, v224
	s_movk_i32 s1, 0x1400
	v_mad_u64_u32 v[156:157], s[98:99], v216, s1, v[112:113]
	global_load_dwordx4 v[196:199], v[156:157], off
	global_load_dwordx4 v[200:203], v[156:157], off offset:32
	global_load_dwordx4 v[204:207], v[156:157], off offset:64
	global_load_dwordx4 v[208:211], v[156:157], off offset:96
	s_cmp_lt_i32 s0, 32
	s_cselect_b32 s1, 2, 1
	s_cmp_lt_i32 s0, 64
	s_cselect_b32 s2, s1, 0
	s_cmp_lt_i32 s0, s33
	s_cselect_b32 s1, 3, 2
	s_cmp_ge_i32 s0, s97
	s_cselect_b32 s3, s1, 4
	s_lshl_b32 s1, s2, 5
	s_add_i32 s0, s0, s1
	s_sub_i32 s80, s0, 64
	v_mov_b32_e32 v212, 0x0
	v_mov_b32_e32 v213, 0
	v_mov_b32_e32 v80, 0
	v_mov_b32_e32 v81, 0
	v_mov_b32_e32 v82, 0
	v_mov_b32_e32 v83, 0
	v_mov_b32_e32 v84, 0
	v_mov_b32_e32 v85, 0
	v_mov_b32_e32 v86, 0
	v_mov_b32_e32 v87, 0
	v_mov_b32_e32 v88, 0
	v_mov_b32_e32 v89, 0
	v_mov_b32_e32 v90, 0
	v_mov_b32_e32 v91, 0
	v_mov_b32_e32 v92, 0
	v_mov_b32_e32 v93, 0
	v_mov_b32_e32 v94, 0
	v_mov_b32_e32 v95, 0
	v_mov_b32_e32 v64, 0
	v_mov_b32_e32 v65, 0
	v_mov_b32_e32 v66, 0
	v_mov_b32_e32 v67, 0
	v_mov_b32_e32 v68, 0
	v_mov_b32_e32 v69, 0
	v_mov_b32_e32 v70, 0
	v_mov_b32_e32 v71, 0
	v_mov_b32_e32 v72, 0
	v_mov_b32_e32 v73, 0
	v_mov_b32_e32 v74, 0
	v_mov_b32_e32 v75, 0
	v_mov_b32_e32 v76, 0
	v_mov_b32_e32 v77, 0
	v_mov_b32_e32 v78, 0
	v_mov_b32_e32 v79, 0
	s_mov_b32 s80, s86
	s_mov_b32 s81, s2
	s_add_i32 s0, s81, 1
	s_min_i32 s0, s80, s0
	s_sub_i32 s1, s0, s80
	s_lshl_b32 s1, s1, 5
	s_add_i32 s75, s75, s1
	s_mov_b32 s86, s0
	s_add_i32 s2, s0, -1
	s_mov_b32 s1, 0xffffdfff
	v_and_b32_e32 v130, s1, v130
	v_and_b32_e32 v131, s1, v131
	v_and_b32_e32 v132, s1, v132
	v_and_b32_e32 v133, s1, v133
	v_and_b32_e32 v134, s1, v134
	s_lshl_b32 s0, s75, s73
	s_add_i32 s0, s0, s74
	s_lshl_b32 s32, s83, 13
	s_mul_i32 s1, s0, 0x1400
	v_readlane_b32 s98, v255, 38
	v_readlane_b32 s99, v255, 39
	s_add_u32 s98, s98, s1
	s_addc_u32 s99, s99, 0
	s_sub_i32 s1, s92, 0x400
	s_mov_b32 m0, s32
	s_nop 0
	global_load_lds_dwordx4 v143, s[98:99]
	s_add_u32 s98, s98, s1
	s_addc_u32 s99, s99, 0
	global_load_lds_dwordx4 v144, s[98:99] offset:1024
	s_add_u32 s98, s98, s1
	s_addc_u32 s99, s99, 0
	global_load_lds_dwordx4 v143, s[98:99] offset:2048
	s_add_u32 s98, s98, s1
	s_addc_u32 s99, s99, 0
	global_load_lds_dwordx4 v144, s[98:99] offset:3072
	s_add_u32 s98, s98, 0x300
	s_addc_u32 s99, s99, 0
	s_add_i32 m0, s32, 0x1000
	s_nop 0
	global_load_lds_dwordx4 v145, s[98:99] offset:3072
	s_sub_u32 s98, s98, s1
	s_subb_u32 s99, s99, 0
	global_load_lds_dwordx4 v145, s[98:99] offset:2048
	s_sub_u32 s98, s98, s1
	s_subb_u32 s99, s99, 0
	global_load_lds_dwordx4 v145, s[98:99] offset:1024
	s_sub_u32 s98, s98, s1
	s_subb_u32 s99, s99, 0
	global_load_lds_dwordx4 v145, s[98:99]
	s_xor_b32 s32, s32, 0x2000
	s_add_i32 s75, s75, 32
	s_lshl_b32 s0, s75, s73
	s_add_i32 s0, s0, s74
	s_lshl_b32 s32, s83, 13
	s_add_i32 s32, s32, 0x2000
	s_mul_i32 s1, s0, 0x1400
	v_readlane_b32 s98, v255, 38
	v_readlane_b32 s99, v255, 39
	s_add_u32 s98, s98, s1
	s_addc_u32 s99, s99, 0
	s_sub_i32 s1, s92, 0x400
	s_mov_b32 m0, s32
	s_nop 0
	global_load_lds_dwordx4 v143, s[98:99]
	s_add_u32 s98, s98, s1
	s_addc_u32 s99, s99, 0
	global_load_lds_dwordx4 v144, s[98:99] offset:1024
	s_add_u32 s98, s98, s1
	s_addc_u32 s99, s99, 0
	global_load_lds_dwordx4 v143, s[98:99] offset:2048
	s_add_u32 s98, s98, s1
	s_addc_u32 s99, s99, 0
	global_load_lds_dwordx4 v144, s[98:99] offset:3072
	s_add_u32 s98, s98, 0x300
	s_addc_u32 s99, s99, 0
	s_add_i32 m0, s32, 0x1000
	s_nop 0
	global_load_lds_dwordx4 v145, s[98:99] offset:3072
	s_sub_u32 s98, s98, s1
	s_subb_u32 s99, s99, 0
	global_load_lds_dwordx4 v145, s[98:99] offset:2048
	s_sub_u32 s98, s98, s1
	s_subb_u32 s99, s99, 0
	global_load_lds_dwordx4 v145, s[98:99] offset:1024
	s_sub_u32 s98, s98, s1
	s_subb_u32 s99, s99, 0
	global_load_lds_dwordx4 v145, s[98:99]
	s_xor_b32 s32, s32, 0x2000
	s_add_i32 s75, s75, 32
; __device__ __forceinline__ void attnA_unit(const Args& a, int unit, LAS unsigned char* lds) {
;     ...
; #pragma unroll 1
;             for (int kt = kt0; kt <= kt1; ++kt) {
;                 asm volatile("" ::: "memory");
;                 lwrite32<true>(wl, pk, lane); lwrite32<false>(wl + 4096, pv, lane);
;                 if (kt < kt1) { const size_t ro = (size_t)(dl * (i0 - 64 + 32 * (kt + 1)) + r) * (PW * 2); gload32(pk, kbase + ro, pitch, lane); gload32(pv, vbase + ro, pitch, lane); }
;                 asm volatile("s_waitcnt lgkmcnt(0)" ::: "memory");
;                 bf16x8 kf[4], vf[2][2];
;                 load_kf(wl, kf, lane); load_vf(wl + 4096, vf, lane);
;                 attn_step<false>(kf, wl, vf, qf, o0, o1, m, l, lane, kt == 0 ? 1 : (kt == 4 ? 2 : 0));
.LaT_loopH:
	s_cmp_lt_i32 s86, s87
	s_cbranch_scc1 .LaT_hw8
	s_add_i32 s0, s2, 1
	s_cmp_le_i32 s0, s3
	s_cbranch_scc1 .LaT_hw8
	s_waitcnt vmcnt(0)
	s_branch .LaT_hw0
.LaT_hw8:
	s_waitcnt vmcnt(8)
.LaT_hw0:
	ds_read_b128 v[160:163], v130
	ds_read_b128 v[164:167], v131
	ds_read_b128 v[168:171], v132
	ds_read_b128 v[172:175], v133
	s_waitcnt lgkmcnt(3)
	v_mfma_f32_32x32x16_bf16 v[32:47], v[160:163], v[48:51], 0
	v_mfma_f32_32x32x16_bf16 v[96:111], v[160:163], v[196:199], 0
	s_waitcnt lgkmcnt(2)
	v_mfma_f32_32x32x16_bf16 v[32:47], v[164:167], v[52:55], v[32:47]
	v_mfma_f32_32x32x16_bf16 v[96:111], v[164:167], v[200:203], v[96:111]
	s_waitcnt lgkmcnt(1)
	v_mfma_f32_32x32x16_bf16 v[32:47], v[168:171], v[56:59], v[32:47]
	v_mfma_f32_32x32x16_bf16 v[96:111], v[168:171], v[204:207], v[96:111]
	s_waitcnt lgkmcnt(0)
	v_mfma_f32_32x32x16_bf16 v[32:47], v[172:175], v[60:63], v[32:47]
	v_mfma_f32_32x32x16_bf16 v[96:111], v[172:175], v[208:211], v[96:111]
	ds_read_b64_tr_b16 v[160:161], v134 offset:4096
	ds_read_b64_tr_b16 v[162:163], v134 offset:5120
	ds_read_b64_tr_b16 v[164:165], v134 offset:4160
	ds_read_b64_tr_b16 v[166:167], v134 offset:5184
	ds_read_b64_tr_b16 v[168:169], v134 offset:6144
	ds_read_b64_tr_b16 v[170:171], v134 offset:7168
	ds_read_b64_tr_b16 v[172:173], v134 offset:6208
	ds_read_b64_tr_b16 v[174:175], v134 offset:7232
	s_nop 7
	s_cmp_lt_i32 s86, s80
	s_cbranch_scc1 .LaT_m3aH
	s_cmp_gt_i32 s86, s87
	s_cbranch_scc1 .LaT_m3aH
	s_cmp_eq_u32 s86, 0
	s_cbranch_scc1 .LaT_m1aH
	s_cmp_eq_u32 s86, 4
	s_cbranch_scc0 .LaT_m0aH
	v_cndmask_b32_e64 v32, v237, v32, s[6:7]
	v_cndmask_b32_e64 v33, v237, v33, s[10:11]
	v_cndmask_b32_e64 v34, v237, v34, s[14:15]
	v_cndmask_b32_e64 v35, v237, v35, s[18:19]
	v_cndmask_b32_e64 v36, v237, v36, s[22:23]
	v_cndmask_b32_e64 v37, v237, v37, s[26:27]
	v_cndmask_b32_e64 v38, v237, v38, s[30:31]
	v_cndmask_b32_e64 v39, v237, v39, s[36:37]
	v_cndmask_b32_e64 v40, v237, v40, s[40:41]
	v_cndmask_b32_e64 v41, v237, v41, s[44:45]
	v_cndmask_b32_e64 v42, v237, v42, s[48:49]
	v_cndmask_b32_e64 v43, v237, v43, s[52:53]
	v_cndmask_b32_e64 v44, v237, v44, s[56:57]
	v_cndmask_b32_e64 v45, v237, v45, s[60:61]
	v_cndmask_b32_e64 v46, v237, v46, s[64:65]
	v_cndmask_b32_e64 v47, v237, v47, s[68:69]
	s_branch .LaT_m0aH

; template <bool KLDS>
; __device__ __forceinline__ void attn_step(const bf16x8 (&kf)[4], LAS const unsigned char* kb, const bf16x8 (&vf)[2][2], const bf16x8 (&qf)[4], f32x16& o0, f32x16& o1, float& m, float& l, int lane, int maskmode) {
;     ...
;     if (maskmode) {
; #pragma unroll
;         for (int i = 0; i < 16; ++i) { const int kr = (i & 3) + 8 * (i >> 2) + 4 * h; const bool ok = (maskmode == 1) ? (kr >= ql) : (kr <= ql); S[i] = ok ? S[i] : -1e30f; }
;     }
.LaT_m0aH:
	s_cmp_lt_i32 s2, s81
	s_cbranch_scc1 .LaT_m3bH
	s_cmp_gt_i32 s2, s3
	s_cbranch_scc1 .LaT_m3bH
	s_cmp_eq_u32 s2, 0
	s_cbranch_scc1 .LaT_m1bH
	s_cmp_eq_u32 s2, 4
	s_cbranch_scc0 .LaT_m0bH
	v_cndmask_b32_e64 v96, v237, v96, s[6:7]
	v_cndmask_b32_e64 v97, v237, v97, s[10:11]
	v_cndmask_b32_e64 v98, v237, v98, s[14:15]
	v_cndmask_b32_e64 v99, v237, v99, s[18:19]
	v_cndmask_b32_e64 v100, v237, v100, s[22:23]
	v_cndmask_b32_e64 v101, v237, v101, s[26:27]
	v_cndmask_b32_e64 v102, v237, v102, s[30:31]
	v_cndmask_b32_e64 v103, v237, v103, s[36:37]
	v_cndmask_b32_e64 v104, v237, v104, s[40:41]
	v_cndmask_b32_e64 v105, v237, v105, s[44:45]
	v_cndmask_b32_e64 v106, v237, v106, s[48:49]
	v_cndmask_b32_e64 v107, v237, v107, s[52:53]
	v_cndmask_b32_e64 v108, v237, v108, s[56:57]
	v_cndmask_b32_e64 v109, v237, v109, s[60:61]
	v_cndmask_b32_e64 v110, v237, v110, s[64:65]
	v_cndmask_b32_e64 v111, v237, v111, s[68:69]
	s_branch .LaT_m0bH

; __device__ __forceinline__ unsigned pk2n(float lo, float hi) { const f32x2v v = {lo, hi}; const bf16v2 b = __builtin_convertvector(v, bf16v2); return __builtin_bit_cast(unsigned, b); }
; __device__ __forceinline__ float fexp2(float x) { return __builtin_amdgcn_exp2f(x); }
; template <bool KLDS>
; __device__ __forceinline__ void attn_step(const bf16x8 (&kf)[4], LAS const unsigned char* kb, const bf16x8 (&vf)[2][2], const bf16x8 (&qf)[4], f32x16& o0, f32x16& o1, float& m, float& l, int lane, int maskmode) {
;     ...
;     const float mn = fmaxf(m, tm), al = fexp2(m - mn); m = mn;
;     float ps = 0.f;
; #pragma unroll
;     for (int i = 0; i < 16; ++i) { S[i] = fexp2(S[i] - mn); ps += S[i]; }
;     l = l * al + ps;
; #pragma unroll
;     for (int i = 0; i < 16; ++i) { o0[i] *= al; o1[i] *= al; }
;     bf16x8 pf[2];
; #pragma unroll
;     for (int s2 = 0; s2 < 2; ++s2) {
;         u32x4 w; w.x = pk2n(S[8 * s2 + 0], S[8 * s2 + 1]); w.y = pk2n(S[8 * s2 + 2], S[8 * s2 + 3]); w.z = pk2n(S[8 * s2 + 4], S[8 * s2 + 5]); w.w = pk2n(S[8 * s2 + 6], S[8 * s2 + 7]);
;         pf[s2] = __builtin_bit_cast(bf16x8, w);
;     }
; #pragma unroll
;     for (int s2 = 0; s2 < 2; ++s2) {
;         o0 = __builtin_amdgcn_mfma_f32_32x32x16_bf16(vf[s2][0], pf[s2], o0, 0, 0, 0);
;         o1 = __builtin_amdgcn_mfma_f32_32x32x16_bf16(vf[s2][1], pf[s2], o1, 0, 0, 0);
;     }
; __device__ __forceinline__ void attnA_unit(const Args& a, int unit, LAS unsigned char* lds) {
;     ...
;             for (int kt = kt0; kt <= kt1; ++kt) {
;                 asm volatile("" ::: "memory");
;                 lwrite32<true>(wl, pk, lane); lwrite32<false>(wl + 4096, pv, lane);
;                 if (kt < kt1) { const size_t ro = (size_t)(dl * (i0 - 64 + 32 * (kt + 1)) + r) * (PW * 2); gload32(pk, kbase + ro, pitch, lane); gload32(pv, vbase + ro, pitch, lane); }
;                 asm volatile("s_waitcnt lgkmcnt(0)" ::: "memory");
;                 bf16x8 kf[4], vf[2][2];
;                 load_kf(wl, kf, lane); load_vf(wl + 4096, vf, lane);
;                 attn_step<false>(kf, wl, vf, qf, o0, o1, m, l, lane, kt == 0 ? 1 : (kt == 4 ? 2 : 0));
;                 asm volatile("" ::: "memory");
.LaT_m0bH:
	s_waitcnt lgkmcnt(0)
	s_add_i32 s0, s86, 2
	s_cmp_le_i32 s0, s87
	s_cbranch_scc1 .LaT_hdo
	s_add_i32 s0, s2, 2
	s_cmp_le_i32 s0, s3
	s_cbranch_scc0 .LaT_hnd
.LaT_hdo:
	v_readfirstlane_b32 s32, v130
	s_and_b32 s32, s32, 0x2000
	s_lshl_b32 s1, s83, 13
	s_add_i32 s32, s32, s1
	s_lshl_b32 s0, s75, s73
	s_add_i32 s0, s0, s74
	s_mul_i32 s1, s0, 0x1400
	v_readlane_b32 s98, v255, 38
	v_readlane_b32 s99, v255, 39
	s_add_u32 s98, s98, s1
	s_addc_u32 s99, s99, 0
	s_sub_i32 s1, s92, 0x400
	s_mov_b32 m0, s32
	s_nop 0
	global_load_lds_dwordx4 v143, s[98:99]
	s_add_u32 s98, s98, s1
	s_addc_u32 s99, s99, 0
	global_load_lds_dwordx4 v144, s[98:99] offset:1024
	s_add_u32 s98, s98, s1
	s_addc_u32 s99, s99, 0
	global_load_lds_dwordx4 v143, s[98:99] offset:2048
	s_add_u32 s98, s98, s1
	s_addc_u32 s99, s99, 0
	global_load_lds_dwordx4 v144, s[98:99] offset:3072
	s_add_u32 s98, s98, 0x300
	s_addc_u32 s99, s99, 0
	s_add_i32 m0, s32, 0x1000
	s_nop 0
	global_load_lds_dwordx4 v145, s[98:99] offset:3072
	s_sub_u32 s98, s98, s1
	s_subb_u32 s99, s99, 0
	global_load_lds_dwordx4 v145, s[98:99] offset:2048
	s_sub_u32 s98, s98, s1
	s_subb_u32 s99, s99, 0
	global_load_lds_dwordx4 v145, s[98:99] offset:1024
	s_sub_u32 s98, s98, s1
	s_subb_u32 s99, s99, 0
	global_load_lds_dwordx4 v145, s[98:99]
	s_xor_b32 s32, s32, 0x2000
.LaT_hnd:
	s_add_i32 s75, s75, 32
	v_xor_b32_e32 v130, 0x2000, v130
	v_xor_b32_e32 v131, 0x2000, v131
	v_xor_b32_e32 v132, 0x2000, v132
	v_xor_b32_e32 v133, 0x2000, v133
	v_xor_b32_e32 v134, 0x2000, v134
	v_exp_f32_e32 v32, v32
	v_exp_f32_e32 v96, v96
	v_exp_f32_e32 v33, v33
	v_exp_f32_e32 v97, v97
	v_exp_f32_e32 v34, v34
	v_exp_f32_e32 v98, v98
	v_add_f32_e32 v152, v32, v33
	v_add_f32_e32 v218, v96, v97
	v_exp_f32_e32 v35, v35
	v_exp_f32_e32 v99, v99
	v_add_f32_e32 v153, v34, v35
	v_add_f32_e32 v219, v98, v99
	v_exp_f32_e32 v36, v36
	v_exp_f32_e32 v100, v100
	v_exp_f32_e32 v37, v37
	v_exp_f32_e32 v101, v101
	v_add_f32_e32 v153, v153, v36
	v_add_f32_e32 v219, v219, v100
	v_exp_f32_e32 v38, v38
	v_exp_f32_e32 v102, v102
	v_add_f32_e32 v152, v152, v37
	v_add_f32_e32 v218, v218, v101
	v_exp_f32_e32 v39, v39
	v_exp_f32_e32 v103, v103
	v_add_f32_e32 v153, v153, v38
	v_add_f32_e32 v219, v219, v102
	v_exp_f32_e32 v40, v40
	v_exp_f32_e32 v104, v104
	v_add_f32_e32 v152, v152, v39
	v_add_f32_e32 v218, v218, v103
	v_exp_f32_e32 v41, v41
	v_exp_f32_e32 v105, v105
	v_add_f32_e32 v153, v153, v40
	v_add_f32_e32 v219, v219, v104
	v_exp_f32_e32 v42, v42
	v_exp_f32_e32 v106, v106
	v_add_f32_e32 v152, v152, v41
	v_add_f32_e32 v218, v218, v105
	v_exp_f32_e32 v43, v43
	v_exp_f32_e32 v107, v107
	v_add_f32_e32 v153, v153, v42
	v_add_f32_e32 v219, v219, v106
	v_exp_f32_e32 v44, v44
	v_exp_f32_e32 v108, v108
	v_add_f32_e32 v152, v152, v43
	v_add_f32_e32 v218, v218, v107
	v_exp_f32_e32 v45, v45
	v_exp_f32_e32 v109, v109
	v_add_f32_e32 v153, v153, v44
	v_add_f32_e32 v219, v219, v108
	v_exp_f32_e32 v46, v46
	v_exp_f32_e32 v110, v110
	v_add_f32_e32 v152, v152, v45
	v_add_f32_e32 v218, v218, v109
	v_exp_f32_e32 v47, v47
	v_exp_f32_e32 v111, v111
	v_add_f32_e32 v153, v153, v46
	v_add_f32_e32 v219, v219, v110
	s_nop 0
	s_nop 0
	v_add_f32_e32 v153, v153, v47
	v_add_f32_e32 v219, v219, v111
	v_add_f32_e32 v152, v152, v153
	v_add_f32_e32 v218, v218, v219
	v_add_f32_e32 v135, v135, v152
	v_add_f32_e32 v213, v213, v218
	v_cvt_pk_bf16_f32 v32, v32, v33
	v_cvt_pk_bf16_f32 v96, v96, v97
	v_cvt_pk_bf16_f32 v33, v34, v35
	v_cvt_pk_bf16_f32 v97, v98, v99
	v_cvt_pk_bf16_f32 v34, v36, v37
	v_cvt_pk_bf16_f32 v98, v100, v101
	v_cvt_pk_bf16_f32 v35, v38, v39
	v_cvt_pk_bf16_f32 v99, v102, v103
	v_cvt_pk_bf16_f32 v36, v40, v41
	v_cvt_pk_bf16_f32 v100, v104, v105
	v_cvt_pk_bf16_f32 v37, v42, v43
	v_cvt_pk_bf16_f32 v101, v106, v107
	v_cvt_pk_bf16_f32 v38, v44, v45
	v_cvt_pk_bf16_f32 v102, v108, v109
	v_cvt_pk_bf16_f32 v39, v46, v47
	v_cvt_pk_bf16_f32 v103, v110, v111
	s_nop 0
	v_mfma_f32_32x32x16_bf16 v[16:31], v[160:163], v[32:35], v[16:31]
	v_mfma_f32_32x32x16_bf16 v[80:95], v[160:163], v[96:99], v[80:95]
	v_mfma_f32_32x32x16_bf16 v[0:15], v[164:167], v[32:35], v[0:15]
	v_mfma_f32_32x32x16_bf16 v[64:79], v[164:167], v[96:99], v[64:79]
	v_mfma_f32_32x32x16_bf16 v[16:31], v[168:171], v[36:39], v[16:31]
	v_mfma_f32_32x32x16_bf16 v[80:95], v[168:171], v[100:103], v[80:95]
	v_mfma_f32_32x32x16_bf16 v[0:15], v[172:175], v[36:39], v[0:15]
	v_mfma_f32_32x32x16_bf16 v[64:79], v[172:175], v[100:103], v[64:79]
	s_add_i32 s86, s86, 1
	s_add_i32 s2, s2, 1
	s_cmp_le_i32 s86, s87
	s_cbranch_scc1 .LaT_loopH
	s_cmp_le_i32 s2, s3
	s_cbranch_scc1 .LaT_loopH
	s_nop 15
	s_nop 7
	s_mov_b32 s1, 0xffffdfff
	v_and_b32_e32 v130, s1, v130
	v_and_b32_e32 v131, s1, v131
	v_and_b32_e32 v132, s1, v132
	v_and_b32_e32 v133, s1, v133
	v_and_b32_e32 v134, s1, v134
	s_branch .LaT_guard
; __device__ __forceinline__ void attnA_unit(const Args& a, int unit, LAS unsigned char* lds) {
;     ...
;             const int qt = 2 * wid + e, r = qt % dl, i0 = (512 * blk) / dl + 32 * (qt / dl);
;             const int tq = dl * (i0 + ql) + r;
;             bf16x8 qf[4];
;             { const bf16_t* qp = P + ((size_t)b * SEQ + tq) * PW + 64 * hh + 8 * h;
; #pragma unroll
;               for (int s = 0; s < 4; ++s) qf[s] = *(const bf16x8*)(qp + 16 * s); }
;             f32x16 o0, o1;
; #pragma unroll
;             for (int i = 0; i < 16; ++i) { o0[i] = 0.f; o1[i] = 0.f; }
;             float m = -1e30f, l = 0.f;
;             int kt0 = 0, kt1 = 4;
;             if (i0 - 64 < 0) kt0 = (i0 - 32 < 0) ? 2 : 1;
;             if (i0 + 64 >= Ls) kt1 = (i0 + 32 >= Ls) ? 2 : 3;
;             const unsigned pitch = (unsigned)dl * (PW * 2);
;             u32x4 pk[4], pv[4];
;             { const size_t ro = (size_t)(dl * (i0 - 64 + 32 * kt0) + r) * (PW * 2); gload32(pk, kbase + ro, pitch, lane); gload32(pv, vbase + ro, pitch, lane); }
.LaT_sep:
	s_lshr_b32 s0, s83, 1
	s_and_b32 s1, s0, 3
	s_lshr_b32 s0, s0, 2
	s_lshl_b32 s0, s0, 3
	s_or_b32 s0, s0, s1
	s_or_b32 s0, s0, 0
	s_or_b32 s1, s83, 0
	s_cmp_eq_u32 s82, 1
	s_cselect_b32 s0, s0, s1
	s_add_i32 s1, s72, -1
	s_and_b32 s74, s0, s1
	s_lshr_b32 s0, s0, s73
	s_lshl_b32 s0, s0, 5
	s_add_i32 s0, s0, s96
	v_add_u32_e32 v122, s0, v124
	v_lshlrev_b32_e32 v122, s73, v122
	v_add_u32_e32 v122, s74, v122
	v_add_u32_e32 v122, s76, v122
	v_mov_b32_e32 v123, 0
	v_add_u32_e32 v142, s0, v125
	v_lshlrev_b32_e32 v142, s73, v142
	v_add_u32_e32 v142, s74, v142
	v_add_u32_e32 v142, s76, v142
	s_movk_i32 s1, 0x1400
	v_mad_u64_u32 v[156:157], s[98:99], v122, s1, v[112:113]
	global_load_dwordx4 v[48:51], v[156:157], off
	global_load_dwordx4 v[52:55], v[156:157], off offset:32
	global_load_dwordx4 v[56:59], v[156:157], off offset:64
	global_load_dwordx4 v[60:63], v[156:157], off offset:96
	s_cmp_lt_i32 s0, 32
	s_cselect_b32 s1, 2, 1
	s_cmp_lt_i32 s0, 64
	s_cselect_b32 s86, s1, 0
	s_cmp_lt_i32 s0, s33
	s_cselect_b32 s1, 3, 2
	s_cmp_ge_i32 s0, s97
	s_cselect_b32 s87, s1, 4
	s_lshl_b32 s1, s86, 5
	s_add_i32 s0, s0, s1
	s_sub_i32 s75, s0, 64
	s_lshl_b32 s0, s75, s73
	s_add_i32 s0, s0, s74
	s_lshl_b32 s32, s83, 13
	s_mul_i32 s1, s0, 0x1400
	v_readlane_b32 s98, v255, 38
	v_readlane_b32 s99, v255, 39
	s_add_u32 s98, s98, s1
	s_addc_u32 s99, s99, 0
	s_sub_i32 s1, s92, 0x400
	s_mov_b32 m0, s32
	s_nop 0
	global_load_lds_dwordx4 v143, s[98:99]
	s_add_u32 s98, s98, s1
	s_addc_u32 s99, s99, 0
	global_load_lds_dwordx4 v144, s[98:99] offset:1024
	s_add_u32 s98, s98, s1
	s_addc_u32 s99, s99, 0
	global_load_lds_dwordx4 v143, s[98:99] offset:2048
	s_add_u32 s98, s98, s1
	s_addc_u32 s99, s99, 0
	global_load_lds_dwordx4 v144, s[98:99] offset:3072
	s_add_u32 s98, s98, 0x300
	s_addc_u32 s99, s99, 0
	s_add_i32 m0, s32, 0x1000
	s_nop 0
	global_load_lds_dwordx4 v145, s[98:99] offset:3072
	s_sub_u32 s98, s98, s1
	s_subb_u32 s99, s99, 0
	global_load_lds_dwordx4 v145, s[98:99] offset:2048
	s_sub_u32 s98, s98, s1
	s_subb_u32 s99, s99, 0
	global_load_lds_dwordx4 v145, s[98:99] offset:1024
	s_sub_u32 s98, s98, s1
	s_subb_u32 s99, s99, 0
	global_load_lds_dwordx4 v145, s[98:99]
	s_xor_b32 s32, s32, 0x2000
	s_add_i32 s75, s75, 32
	v_mov_b32_e32 v137, 0x0
	v_mov_b32_e32 v135, 0
	v_mov_b32_e32 v16, 0
	v_mov_b32_e32 v17, 0
	v_mov_b32_e32 v18, 0
	v_mov_b32_e32 v19, 0
	v_mov_b32_e32 v20, 0
	v_mov_b32_e32 v21, 0
	v_mov_b32_e32 v22, 0
	v_mov_b32_e32 v23, 0
	v_mov_b32_e32 v24, 0
	v_mov_b32_e32 v25, 0
	v_mov_b32_e32 v26, 0
	v_mov_b32_e32 v27, 0
	v_mov_b32_e32 v28, 0
	v_mov_b32_e32 v29, 0
	v_mov_b32_e32 v30, 0
	v_mov_b32_e32 v31, 0
	v_mov_b32_e32 v0, 0
	v_mov_b32_e32 v1, 0
	v_mov_b32_e32 v2, 0
	v_mov_b32_e32 v3, 0
	v_mov_b32_e32 v4, 0
	v_mov_b32_e32 v5, 0
	v_mov_b32_e32 v6, 0
	v_mov_b32_e32 v7, 0
	v_mov_b32_e32 v8, 0
	v_mov_b32_e32 v9, 0
	v_mov_b32_e32 v10, 0
	v_mov_b32_e32 v11, 0
	v_mov_b32_e32 v12, 0
	v_mov_b32_e32 v13, 0
	v_mov_b32_e32 v14, 0
	v_mov_b32_e32 v15, 0
	s_lshr_b32 s0, s83, 1
	s_and_b32 s1, s0, 3
	s_lshr_b32 s0, s0, 2
	s_lshl_b32 s0, s0, 3
	s_or_b32 s0, s0, s1
	s_or_b32 s0, s0, 4
	s_or_b32 s1, s83, 1
	s_cmp_eq_u32 s82, 1
	s_cselect_b32 s0, s0, s1
	s_add_i32 s1, s72, -1
	s_and_b32 s81, s0, s1
	s_lshr_b32 s0, s0, s73
	s_lshl_b32 s0, s0, 5
	s_add_i32 s0, s0, s96
	v_add_u32_e32 v216, s0, v124
	v_lshlrev_b32_e32 v216, s73, v216
	v_add_u32_e32 v216, s81, v216
	v_add_u32_e32 v216, s76, v216
	v_mov_b32_e32 v217, 0
	v_add_u32_e32 v224, s0, v125
	v_lshlrev_b32_e32 v224, s73, v224
	v_add_u32_e32 v224, s81, v224
	v_add_u32_e32 v224, s76, v224
	s_movk_i32 s1, 0x1400
	v_mad_u64_u32 v[156:157], s[98:99], v216, s1, v[112:113]
	global_load_dwordx4 v[196:199], v[156:157], off
	global_load_dwordx4 v[200:203], v[156:157], off offset:32
	global_load_dwordx4 v[204:207], v[156:157], off offset:64
	global_load_dwordx4 v[208:211], v[156:157], off offset:96
	s_cmp_lt_i32 s0, 32
	s_cselect_b32 s1, 2, 1
	s_cmp_lt_i32 s0, 64
	s_cselect_b32 s2, s1, 0
	s_cmp_lt_i32 s0, s33
	s_cselect_b32 s1, 3, 2
	s_cmp_ge_i32 s0, s97
	s_cselect_b32 s3, s1, 4
	s_lshl_b32 s1, s2, 5
	s_add_i32 s0, s0, s1
	s_sub_i32 s80, s0, 64
	s_lshl_b32 s0, s80, s73
	s_add_i32 s0, s0, s81
	s_lshl_b32 s32, s83, 13
	s_add_i32 s32, s32, 0x2000
	s_mul_i32 s1, s0, 0x1400
	v_readlane_b32 s98, v255, 38
	v_readlane_b32 s99, v255, 39
	s_add_u32 s98, s98, s1
	s_addc_u32 s99, s99, 0
	s_sub_i32 s1, s92, 0x400
	s_mov_b32 m0, s32
	s_nop 0
	global_load_lds_dwordx4 v143, s[98:99]
	s_add_u32 s98, s98, s1
	s_addc_u32 s99, s99, 0
	global_load_lds_dwordx4 v144, s[98:99] offset:1024
	s_add_u32 s98, s98, s1
	s_addc_u32 s99, s99, 0
	global_load_lds_dwordx4 v143, s[98:99] offset:2048
	s_add_u32 s98, s98, s1
	s_addc_u32 s99, s99, 0
	global_load_lds_dwordx4 v144, s[98:99] offset:3072
	s_add_u32 s98, s98, 0x300
	s_addc_u32 s99, s99, 0
	s_add_i32 m0, s32, 0x1000
	s_nop 0
	global_load_lds_dwordx4 v145, s[98:99] offset:3072
	s_sub_u32 s98, s98, s1
	s_subb_u32 s99, s99, 0
	global_load_lds_dwordx4 v145, s[98:99] offset:2048
	s_sub_u32 s98, s98, s1
	s_subb_u32 s99, s99, 0
	global_load_lds_dwordx4 v145, s[98:99] offset:1024
	s_sub_u32 s98, s98, s1
	s_subb_u32 s99, s99, 0
	global_load_lds_dwordx4 v145, s[98:99]
	s_xor_b32 s32, s32, 0x2000
	s_add_i32 s80, s80, 32
	v_mov_b32_e32 v212, 0x0
	v_mov_b32_e32 v213, 0
	v_mov_b32_e32 v80, 0
	v_mov_b32_e32 v81, 0
	v_mov_b32_e32 v82, 0
	v_mov_b32_e32 v83, 0
	v_mov_b32_e32 v84, 0
	v_mov_b32_e32 v85, 0
	v_mov_b32_e32 v86, 0
	v_mov_b32_e32 v87, 0
	v_mov_b32_e32 v88, 0
	v_mov_b32_e32 v89, 0
	v_mov_b32_e32 v90, 0
	v_mov_b32_e32 v91, 0
	v_mov_b32_e32 v92, 0
	v_mov_b32_e32 v93, 0
	v_mov_b32_e32 v94, 0
	v_mov_b32_e32 v95, 0
	v_mov_b32_e32 v64, 0
	v_mov_b32_e32 v65, 0
	v_mov_b32_e32 v66, 0
	v_mov_b32_e32 v67, 0
	v_mov_b32_e32 v68, 0
	v_mov_b32_e32 v69, 0
	v_mov_b32_e32 v70, 0
	v_mov_b32_e32 v71, 0
	v_mov_b32_e32 v72, 0
	v_mov_b32_e32 v73, 0
	v_mov_b32_e32 v74, 0
	v_mov_b32_e32 v75, 0
	v_mov_b32_e32 v76, 0
	v_mov_b32_e32 v77, 0
	v_mov_b32_e32 v78, 0
	v_mov_b32_e32 v79, 0

; __device__ __forceinline__ unsigned pk2(float lo, float hi) { unsigned r; asm("v_cvt_pk_bf16_f32 %0, %1, %2" : "=v"(r) : "v"(lo), "v"(hi)); return r; }
; __device__ __forceinline__ float fexp2(float x) { return __builtin_amdgcn_exp2f(x); }
; template <bool KLDS>
; __device__ __forceinline__ void attn_step(const bf16x8 (&kf)[4], LAS const unsigned char* kb, const bf16x8 (&vf)[2][2], const bf16x8 (&qf)[4], f32x16& o0, f32x16& o1, float& m, float& l, int lane, int maskmode) {
;     ...
;     float tm = S[0];
; #pragma unroll
;     for (int i = 1; i < 16; ++i) tm = fmaxf(tm, S[i]);
;     tm = fmaxf(tm, __shfl_xor(tm, 32));
;     const float mn = fmaxf(m, tm), al = fexp2(m - mn); m = mn;
;     float ps = 0.f;
; #pragma unroll
;     for (int i = 0; i < 16; ++i) { S[i] = fexp2(S[i] - mn); ps += S[i]; }
;     l = l * al + ps;
; #pragma unroll
;     for (int i = 0; i < 16; ++i) { o0[i] *= al; o1[i] *= al; }
;     bf16x8 pf[2];
; #pragma unroll
;     for (int s2 = 0; s2 < 2; ++s2) {
;         u32x4 w; w.x = pk2n(S[8 * s2 + 0], S[8 * s2 + 1]); w.y = pk2n(S[8 * s2 + 2], S[8 * s2 + 3]); w.z = pk2n(S[8 * s2 + 4], S[8 * s2 + 5]); w.w = pk2n(S[8 * s2 + 6], S[8 * s2 + 7]);
;         pf[s2] = __builtin_bit_cast(bf16x8, w);
;     }
; #pragma unroll
;     for (int s2 = 0; s2 < 2; ++s2) {
;         o0 = __builtin_amdgcn_mfma_f32_32x32x16_bf16(vf[s2][0], pf[s2], o0, 0, 0, 0);
;         o1 = __builtin_amdgcn_mfma_f32_32x32x16_bf16(vf[s2][1], pf[s2], o1, 0, 0, 0);
;     }
; __device__ __forceinline__ void attnA_unit(const Args& a, int unit, LAS unsigned char* lds) {
;     ...
;             const float lt = l + __shfl_xor(l, 32);
;             const float inv = 1.0f / lt, lse = m + __builtin_amdgcn_logf(lt);
;             const size_t tokg = (size_t)b * SEQ + tq;
;             if (pidx < 2) {
;                 bf16_t* op = OA + ((size_t)pidx * MTOK + tokg) * 384 + 64 * hh;
; #pragma unroll
;                 for (int dt = 0; dt < 2; ++dt)
; #pragma unroll
;                     for (int g = 0; g < 4; ++g) {
;                         const f32x16& o = dt ? o1 : o0;
;                         u32x2 w; w.x = pk2(o[4 * g] * inv, o[4 * g + 1] * inv); w.y = pk2(o[4 * g + 2] * inv, o[4 * g + 3] * inv);
;                         *(u32x2*)(op + 32 * dt + 8 * g + 4 * h) = w;
;                     }
;                 if (h == 0) LSE[((size_t)pidx * MTOK + tokg) * 6 + hh] = lse;
.LaT_ndbR:
	s_add_i32 s80, s80, 32
	v_exp_f32_e32 v32, v32
	v_exp_f32_e32 v96, v96
	v_exp_f32_e32 v33, v33
	v_exp_f32_e32 v97, v97
	v_exp_f32_e32 v34, v34
	v_exp_f32_e32 v98, v98
	v_add_f32_e32 v152, v32, v33
	v_add_f32_e32 v218, v96, v97
	v_exp_f32_e32 v35, v35
	v_exp_f32_e32 v99, v99
	v_add_f32_e32 v153, v34, v35
	v_add_f32_e32 v219, v98, v99
	v_exp_f32_e32 v36, v36
	v_exp_f32_e32 v100, v100
	v_exp_f32_e32 v37, v37
	v_exp_f32_e32 v101, v101
	v_add_f32_e32 v153, v153, v36
	v_add_f32_e32 v219, v219, v100
	v_exp_f32_e32 v38, v38
	v_exp_f32_e32 v102, v102
	v_add_f32_e32 v152, v152, v37
	v_add_f32_e32 v218, v218, v101
	v_exp_f32_e32 v39, v39
	v_exp_f32_e32 v103, v103
	v_add_f32_e32 v153, v153, v38
	v_add_f32_e32 v219, v219, v102
	v_exp_f32_e32 v40, v40
	v_exp_f32_e32 v104, v104
	v_add_f32_e32 v152, v152, v39
	v_add_f32_e32 v218, v218, v103
	v_exp_f32_e32 v41, v41
	v_exp_f32_e32 v105, v105
	v_add_f32_e32 v153, v153, v40
	v_add_f32_e32 v219, v219, v104
	v_exp_f32_e32 v42, v42
	v_exp_f32_e32 v106, v106
	v_add_f32_e32 v152, v152, v41
	v_add_f32_e32 v218, v218, v105
	v_exp_f32_e32 v43, v43
	v_exp_f32_e32 v107, v107
	v_add_f32_e32 v153, v153, v42
	v_add_f32_e32 v219, v219, v106
	v_exp_f32_e32 v44, v44
	v_exp_f32_e32 v108, v108
	v_add_f32_e32 v152, v152, v43
	v_add_f32_e32 v218, v218, v107
	v_exp_f32_e32 v45, v45
	v_exp_f32_e32 v109, v109
	v_add_f32_e32 v153, v153, v44
	v_add_f32_e32 v219, v219, v108
	v_exp_f32_e32 v46, v46
	v_exp_f32_e32 v110, v110
	v_add_f32_e32 v152, v152, v45
	v_add_f32_e32 v218, v218, v109
	v_exp_f32_e32 v47, v47
	v_exp_f32_e32 v111, v111
	v_add_f32_e32 v153, v153, v46
	v_add_f32_e32 v219, v219, v110
	s_nop 0
	s_nop 0
	v_add_f32_e32 v153, v153, v47
	v_add_f32_e32 v219, v219, v111
	v_add_f32_e32 v152, v152, v153
	v_add_f32_e32 v218, v218, v219
	v_add_f32_e32 v135, v135, v152
	v_add_f32_e32 v213, v213, v218
	v_cvt_pk_bf16_f32 v32, v32, v33
	v_cvt_pk_bf16_f32 v96, v96, v97
	v_cvt_pk_bf16_f32 v33, v34, v35
	v_cvt_pk_bf16_f32 v97, v98, v99
	v_cvt_pk_bf16_f32 v34, v36, v37
	v_cvt_pk_bf16_f32 v98, v100, v101
	v_cvt_pk_bf16_f32 v35, v38, v39
	v_cvt_pk_bf16_f32 v99, v102, v103
	v_cvt_pk_bf16_f32 v36, v40, v41
	v_cvt_pk_bf16_f32 v100, v104, v105
	v_cvt_pk_bf16_f32 v37, v42, v43
	v_cvt_pk_bf16_f32 v101, v106, v107
	v_cvt_pk_bf16_f32 v38, v44, v45
	v_cvt_pk_bf16_f32 v102, v108, v109
	v_cvt_pk_bf16_f32 v39, v46, v47
	v_cvt_pk_bf16_f32 v103, v110, v111
	s_nop 0
	v_mfma_f32_32x32x16_bf16 v[16:31], v[160:163], v[32:35], v[16:31]
	v_mfma_f32_32x32x16_bf16 v[80:95], v[176:179], v[96:99], v[80:95]
	v_mfma_f32_32x32x16_bf16 v[0:15], v[164:167], v[32:35], v[0:15]
	v_mfma_f32_32x32x16_bf16 v[64:79], v[180:183], v[96:99], v[64:79]
	v_mfma_f32_32x32x16_bf16 v[16:31], v[168:171], v[36:39], v[16:31]
	v_mfma_f32_32x32x16_bf16 v[80:95], v[184:187], v[100:103], v[80:95]
	v_mfma_f32_32x32x16_bf16 v[0:15], v[172:175], v[36:39], v[0:15]
	v_mfma_f32_32x32x16_bf16 v[64:79], v[188:191], v[100:103], v[64:79]
	s_add_i32 s86, s86, 1
	s_add_i32 s2, s2, 1
	s_cmp_le_u32 s86, s87
	s_cbranch_scc1 .LaT_loopR
	s_cmp_le_u32 s2, s3
	s_cbranch_scc1 .LaT_loopR
	s_nop 15
	s_nop 7
.LaT_guard:
	s_movk_i32 s0, 0x2ff
	v_mov_b32_e32 v138, v135
	v_mov_b32_e32 v139, v135
	s_nop 1
	v_permlane32_swap_b32_e32 v138, v139
	v_add_f32_e32 v138, v138, v139
	v_mov_b32_e32 v148, v213
	v_mov_b32_e32 v149, v213
	s_nop 1
	v_permlane32_swap_b32_e32 v148, v149
	v_add_f32_e32 v148, v148, v149
	s_movk_i32 s32, 0x2ff
	v_cmp_class_f32_e64 s[0:1], v138, s32
	v_cmp_class_f32_e64 s[98:99], v148, s32
	s_nop 0
	s_or_b64 vcc, s[0:1], s[98:99]
	s_cbranch_vccnz .LaT_safe
.LaT_epi:
	s_lshl_b32 s32, s83, 13
	v_mov_b32_e32 v39, v135
	s_nop 1
	v_permlane32_swap_b32_e32 v39, v135
	v_add_f32_e32 v63, v135, v39
	v_add_u32_e32 v40, s32, v192
	v_log_f32_e32 v34, v63
	v_div_scale_f32 v35, s[0:1], v63, v63, 1.0
	v_rcp_f32_e32 v37, v35
	v_div_scale_f32 v38, vcc, 1.0, v63, 1.0
	v_fma_f32 v62, -v35, v37, 1.0
	v_fmac_f32_e32 v37, v62, v37
	v_mul_f32_e32 v62, v38, v37
	v_fma_f32 v33, -v35, v62, v38
	v_fmac_f32_e32 v62, v33, v37
	v_fma_f32 v35, -v35, v62, v38
	v_div_fmas_f32 v35, v35, v37, v62
	v_div_fixup_f32 v33, v35, v63, 1.0
	v_add_f32_e32 v36, v137, v34
	s_lshl_b32 s80, 8, s73
	s_and_b64 vcc, exec, s[90:91]
	s_cbranch_vccz .LaT_mga
	v_mul_f32_e32 v52, v16, v33
	v_mul_f32_e32 v53, v17, v33
	v_mul_f32_e32 v54, v18, v33
	v_mul_f32_e32 v55, v19, v33
	v_cvt_pk_bf16_f32 v48, v52, v53
	v_cvt_pk_bf16_f32 v49, v54, v55
	v_xor_b32_e32 v41, 0x0, v40
	ds_write_b64 v41, v[48:49]
	v_mul_f32_e32 v52, v20, v33
	v_mul_f32_e32 v53, v21, v33
	v_mul_f32_e32 v54, v22, v33
	v_mul_f32_e32 v55, v23, v33
	v_cvt_pk_bf16_f32 v50, v52, v53
	v_cvt_pk_bf16_f32 v51, v54, v55
	v_xor_b32_e32 v41, 0x10, v40
	ds_write_b64 v41, v[50:51]
	v_mul_f32_e32 v52, v24, v33
	v_mul_f32_e32 v53, v25, v33
	v_mul_f32_e32 v54, v26, v33
	v_mul_f32_e32 v55, v27, v33
	v_cvt_pk_bf16_f32 v48, v52, v53
	v_cvt_pk_bf16_f32 v49, v54, v55
	v_xor_b32_e32 v41, 0x20, v40
	ds_write_b64 v41, v[48:49]
	v_mul_f32_e32 v52, v28, v33
	v_mul_f32_e32 v53, v29, v33
	v_mul_f32_e32 v54, v30, v33
	v_mul_f32_e32 v55, v31, v33
	v_cvt_pk_bf16_f32 v50, v52, v53
	v_cvt_pk_bf16_f32 v51, v54, v55
	v_xor_b32_e32 v41, 0x30, v40
	ds_write_b64 v41, v[50:51]
	v_mul_f32_e32 v52, v0, v33
	v_mul_f32_e32 v53, v1, v33
	v_mul_f32_e32 v54, v2, v33
	v_mul_f32_e32 v55, v3, v33
	v_cvt_pk_bf16_f32 v48, v52, v53
	v_cvt_pk_bf16_f32 v49, v54, v55
	v_xor_b32_e32 v41, 0x40, v40
	ds_write_b64 v41, v[48:49]
	v_mul_f32_e32 v52, v4, v33
	v_mul_f32_e32 v53, v5, v33
	v_mul_f32_e32 v54, v6, v33
	v_mul_f32_e32 v55, v7, v33
	v_cvt_pk_bf16_f32 v50, v52, v53
	v_cvt_pk_bf16_f32 v51, v54, v55
	v_xor_b32_e32 v41, 0x50, v40
	ds_write_b64 v41, v[50:51]
	v_mul_f32_e32 v52, v8, v33
	v_mul_f32_e32 v53, v9, v33
	v_mul_f32_e32 v54, v10, v33
	v_mul_f32_e32 v55, v11, v33
	v_cvt_pk_bf16_f32 v48, v52, v53
	v_cvt_pk_bf16_f32 v49, v54, v55
	v_xor_b32_e32 v41, 0x60, v40
	ds_write_b64 v41, v[48:49]
	v_mul_f32_e32 v52, v12, v33
	v_mul_f32_e32 v53, v13, v33
	v_mul_f32_e32 v54, v14, v33
	v_mul_f32_e32 v55, v15, v33
	v_cvt_pk_bf16_f32 v50, v52, v53
	v_cvt_pk_bf16_f32 v51, v54, v55
	v_xor_b32_e32 v41, 0x70, v40
	ds_write_b64 v41, v[50:51]
	v_readlane_b32 s0, v253, 6
	s_movk_i32 s1, 0x300
	v_add_u32_e32 v43, s0, v142
	v_add_u32_e32 v56, s0, v122
	v_mov_b32_e32 v44, s94
	v_mov_b32_e32 v45, s95
	v_add_co_u32_e32 v44, vcc, v44, v147
	s_nop 0
	v_addc_co_u32_e32 v45, vcc, 0, v45, vcc
	s_and_saveexec_b64 s[2:3], s[70:71]
	v_mad_u64_u32 v[58:59], s[98:99], v56, 24, s[88:89]
	global_store_dword v[58:59], v36, off
	s_or_b64 exec, exec, s[2:3]
	s_branch .LaT_fla

; __device__ __forceinline__ void attnA_unit(const Args& a, int unit, LAS unsigned char* lds) {
;     ...
;             const int qt = 2 * wid + e, r = qt % dl, i0 = (512 * blk) / dl + 32 * (qt / dl);
;             const int tq = dl * (i0 + ql) + r;
;             bf16x8 qf[4];
;             { const bf16_t* qp = P + ((size_t)b * SEQ + tq) * PW + 64 * hh + 8 * h;
; #pragma unroll
;               for (int s = 0; s < 4; ++s) qf[s] = *(const bf16x8*)(qp + 16 * s); }
;             f32x16 o0, o1;
; #pragma unroll
;             for (int i = 0; i < 16; ++i) { o0[i] = 0.f; o1[i] = 0.f; }
;             float m = -1e30f, l = 0.f;
;             int kt0 = 0, kt1 = 4;
;             if (i0 - 64 < 0) kt0 = (i0 - 32 < 0) ? 2 : 1;
;             if (i0 + 64 >= Ls) kt1 = (i0 + 32 >= Ls) ? 2 : 3;
;             const unsigned pitch = (unsigned)dl * (PW * 2);
;             u32x4 pk[4], pv[4];
;             { const size_t ro = (size_t)(dl * (i0 - 64 + 32 * kt0) + r) * (PW * 2); gload32(pk, kbase + ro, pitch, lane); gload32(pv, vbase + ro, pitch, lane); }
.LaT_safe:
	s_lshr_b32 s0, s83, 1
	s_and_b32 s1, s0, 3
	s_lshr_b32 s0, s0, 2
	s_lshl_b32 s0, s0, 3
	s_or_b32 s0, s0, s1
	s_or_b32 s0, s0, 0
	s_or_b32 s1, s83, 0
	s_cmp_eq_u32 s82, 1
	s_cselect_b32 s0, s0, s1
	s_add_i32 s1, s72, -1
	s_and_b32 s74, s0, s1
	s_lshr_b32 s0, s0, s73
	s_lshl_b32 s0, s0, 5
	s_add_i32 s0, s0, s96
	v_add_u32_e32 v122, s0, v124
	v_lshlrev_b32_e32 v122, s73, v122
	v_add_u32_e32 v122, s74, v122
	v_add_u32_e32 v122, s76, v122
	v_mov_b32_e32 v123, 0
	v_add_u32_e32 v142, s0, v125
	v_lshlrev_b32_e32 v142, s73, v142
	v_add_u32_e32 v142, s74, v142
	v_add_u32_e32 v142, s76, v142
	s_movk_i32 s1, 0x1400
	v_mad_u64_u32 v[156:157], s[98:99], v122, s1, v[112:113]
	global_load_dwordx4 v[48:51], v[156:157], off
	global_load_dwordx4 v[52:55], v[156:157], off offset:32
	global_load_dwordx4 v[56:59], v[156:157], off offset:64
	global_load_dwordx4 v[60:63], v[156:157], off offset:96
	s_cmp_lt_i32 s0, 32
	s_cselect_b32 s1, 2, 1
	s_cmp_lt_i32 s0, 64
	s_cselect_b32 s86, s1, 0
	s_cmp_lt_i32 s0, s33
	s_cselect_b32 s1, 3, 2
	s_cmp_ge_i32 s0, s97
	s_cselect_b32 s87, s1, 4
	s_lshl_b32 s1, s86, 5
	s_add_i32 s0, s0, s1
	s_sub_i32 s75, s0, 64
	s_lshl_b32 s0, s75, s73
	s_add_i32 s0, s0, s74
	s_lshl_b32 s32, s83, 13
	s_mul_i32 s1, s0, 0x1400
	v_readlane_b32 s98, v255, 38
	v_readlane_b32 s99, v255, 39
	s_add_u32 s98, s98, s1
	s_addc_u32 s99, s99, 0
	s_sub_i32 s1, s92, 0x400
	s_mov_b32 m0, s32
	s_nop 0
	global_load_lds_dwordx4 v143, s[98:99]
	s_add_u32 s98, s98, s1
	s_addc_u32 s99, s99, 0
	global_load_lds_dwordx4 v144, s[98:99] offset:1024
	s_add_u32 s98, s98, s1
	s_addc_u32 s99, s99, 0
	global_load_lds_dwordx4 v143, s[98:99] offset:2048
	s_add_u32 s98, s98, s1
	s_addc_u32 s99, s99, 0
	global_load_lds_dwordx4 v144, s[98:99] offset:3072
	s_add_u32 s98, s98, 0x300
	s_addc_u32 s99, s99, 0
	s_add_i32 m0, s32, 0x1000
	s_nop 0
	global_load_lds_dwordx4 v145, s[98:99] offset:3072
	s_sub_u32 s98, s98, s1
	s_subb_u32 s99, s99, 0
	global_load_lds_dwordx4 v145, s[98:99] offset:2048
	s_sub_u32 s98, s98, s1
	s_subb_u32 s99, s99, 0
	global_load_lds_dwordx4 v145, s[98:99] offset:1024
	s_sub_u32 s98, s98, s1
	s_subb_u32 s99, s99, 0
	global_load_lds_dwordx4 v145, s[98:99]
	s_xor_b32 s32, s32, 0x2000
	s_add_i32 s75, s75, 32
	v_mov_b32_e32 v137, 0xf149f2ca
	v_mov_b32_e32 v135, 0
	v_mov_b32_e32 v16, 0
	v_mov_b32_e32 v17, 0
	v_mov_b32_e32 v18, 0
	v_mov_b32_e32 v19, 0
	v_mov_b32_e32 v20, 0
	v_mov_b32_e32 v21, 0
	v_mov_b32_e32 v22, 0
	v_mov_b32_e32 v23, 0
	v_mov_b32_e32 v24, 0
	v_mov_b32_e32 v25, 0
	v_mov_b32_e32 v26, 0
	v_mov_b32_e32 v27, 0
	v_mov_b32_e32 v28, 0
	v_mov_b32_e32 v29, 0
	v_mov_b32_e32 v30, 0
	v_mov_b32_e32 v31, 0
	v_mov_b32_e32 v0, 0
	v_mov_b32_e32 v1, 0
	v_mov_b32_e32 v2, 0
	v_mov_b32_e32 v3, 0
	v_mov_b32_e32 v4, 0
	v_mov_b32_e32 v5, 0
	v_mov_b32_e32 v6, 0
	v_mov_b32_e32 v7, 0
	v_mov_b32_e32 v8, 0
	v_mov_b32_e32 v9, 0
	v_mov_b32_e32 v10, 0
	v_mov_b32_e32 v11, 0
	v_mov_b32_e32 v12, 0
	v_mov_b32_e32 v13, 0
	v_mov_b32_e32 v14, 0
	v_mov_b32_e32 v15, 0
	s_lshr_b32 s0, s83, 1
	s_and_b32 s1, s0, 3
	s_lshr_b32 s0, s0, 2
	s_lshl_b32 s0, s0, 3
	s_or_b32 s0, s0, s1
	s_or_b32 s0, s0, 4
	s_or_b32 s1, s83, 1
	s_cmp_eq_u32 s82, 1
	s_cselect_b32 s0, s0, s1
	s_add_i32 s1, s72, -1
	s_and_b32 s81, s0, s1
	s_lshr_b32 s0, s0, s73
	s_lshl_b32 s0, s0, 5
	s_add_i32 s0, s0, s96
	v_add_u32_e32 v216, s0, v124
	v_lshlrev_b32_e32 v216, s73, v216
	v_add_u32_e32 v216, s81, v216
	v_add_u32_e32 v216, s76, v216
	v_mov_b32_e32 v217, 0
	v_add_u32_e32 v224, s0, v125
	v_lshlrev_b32_e32 v224, s73, v224
	v_add_u32_e32 v224, s81, v224
	v_add_u32_e32 v224, s76, v224
	s_movk_i32 s1, 0x1400
	v_mad_u64_u32 v[156:157], s[98:99], v216, s1, v[112:113]
	global_load_dwordx4 v[196:199], v[156:157], off
	global_load_dwordx4 v[200:203], v[156:157], off offset:32
	global_load_dwordx4 v[204:207], v[156:157], off offset:64
	global_load_dwordx4 v[208:211], v[156:157], off offset:96
	s_cmp_lt_i32 s0, 32
	s_cselect_b32 s1, 2, 1
	s_cmp_lt_i32 s0, 64
	s_cselect_b32 s2, s1, 0
	s_cmp_lt_i32 s0, s33
	s_cselect_b32 s1, 3, 2
	s_cmp_ge_i32 s0, s97
	s_cselect_b32 s3, s1, 4
	s_lshl_b32 s1, s2, 5
	s_add_i32 s0, s0, s1
	s_sub_i32 s80, s0, 64
	s_lshl_b32 s0, s80, s73
	s_add_i32 s0, s0, s81
	s_lshl_b32 s32, s83, 13
	s_add_i32 s32, s32, 0x2000
	s_mul_i32 s1, s0, 0x1400
	v_readlane_b32 s98, v255, 38
	v_readlane_b32 s99, v255, 39
	s_add_u32 s98, s98, s1
	s_addc_u32 s99, s99, 0
	s_sub_i32 s1, s92, 0x400
	s_mov_b32 m0, s32
	s_nop 0
	global_load_lds_dwordx4 v143, s[98:99]
	s_add_u32 s98, s98, s1
	s_addc_u32 s99, s99, 0
	global_load_lds_dwordx4 v144, s[98:99] offset:1024
	s_add_u32 s98, s98, s1
	s_addc_u32 s99, s99, 0
	global_load_lds_dwordx4 v143, s[98:99] offset:2048
	s_add_u32 s98, s98, s1
	s_addc_u32 s99, s99, 0
	global_load_lds_dwordx4 v144, s[98:99] offset:3072
	s_add_u32 s98, s98, 0x300
	s_addc_u32 s99, s99, 0
	s_add_i32 m0, s32, 0x1000
	s_nop 0
	global_load_lds_dwordx4 v145, s[98:99] offset:3072
	s_sub_u32 s98, s98, s1
	s_subb_u32 s99, s99, 0
	global_load_lds_dwordx4 v145, s[98:99] offset:2048
	s_sub_u32 s98, s98, s1
	s_subb_u32 s99, s99, 0
	global_load_lds_dwordx4 v145, s[98:99] offset:1024
	s_sub_u32 s98, s98, s1
	s_subb_u32 s99, s99, 0
	global_load_lds_dwordx4 v145, s[98:99]
	s_xor_b32 s32, s32, 0x2000
	s_add_i32 s80, s80, 32
	v_mov_b32_e32 v212, 0xf149f2ca
	v_mov_b32_e32 v213, 0
	v_mov_b32_e32 v80, 0
	v_mov_b32_e32 v81, 0
	v_mov_b32_e32 v82, 0
	v_mov_b32_e32 v83, 0
	v_mov_b32_e32 v84, 0
	v_mov_b32_e32 v85, 0
	v_mov_b32_e32 v86, 0
	v_mov_b32_e32 v87, 0
	v_mov_b32_e32 v88, 0
	v_mov_b32_e32 v89, 0
	v_mov_b32_e32 v90, 0
	v_mov_b32_e32 v91, 0
	v_mov_b32_e32 v92, 0
	v_mov_b32_e32 v93, 0
	v_mov_b32_e32 v94, 0
	v_mov_b32_e32 v95, 0
	v_mov_b32_e32 v64, 0
	v_mov_b32_e32 v65, 0
	v_mov_b32_e32 v66, 0
	v_mov_b32_e32 v67, 0
	v_mov_b32_e32 v68, 0
	v_mov_b32_e32 v69, 0
	v_mov_b32_e32 v70, 0
	v_mov_b32_e32 v71, 0
	v_mov_b32_e32 v72, 0
	v_mov_b32_e32 v73, 0
	v_mov_b32_e32 v74, 0
	v_mov_b32_e32 v75, 0
	v_mov_b32_e32 v76, 0
	v_mov_b32_e32 v77, 0
	v_mov_b32_e32 v78, 0
	v_mov_b32_e32 v79, 0

; __device__ __forceinline__ unsigned pk2n(float lo, float hi) { const f32x2v v = {lo, hi}; const bf16v2 b = __builtin_convertvector(v, bf16v2); return __builtin_bit_cast(unsigned, b); }
; __device__ __forceinline__ float fexp2(float x) { return __builtin_amdgcn_exp2f(x); }
; template <bool KLDS>
; __device__ __forceinline__ void attn_step(const bf16x8 (&kf)[4], LAS const unsigned char* kb, const bf16x8 (&vf)[2][2], const bf16x8 (&qf)[4], f32x16& o0, f32x16& o1, float& m, float& l, int lane, int maskmode) {
;     ...
;     const float mn = fmaxf(m, tm), al = fexp2(m - mn); m = mn;
;     float ps = 0.f;
; #pragma unroll
;     for (int i = 0; i < 16; ++i) { S[i] = fexp2(S[i] - mn); ps += S[i]; }
;     l = l * al + ps;
; #pragma unroll
;     for (int i = 0; i < 16; ++i) { o0[i] *= al; o1[i] *= al; }
;     bf16x8 pf[2];
; #pragma unroll
;     for (int s2 = 0; s2 < 2; ++s2) {
;         u32x4 w; w.x = pk2n(S[8 * s2 + 0], S[8 * s2 + 1]); w.y = pk2n(S[8 * s2 + 2], S[8 * s2 + 3]); w.z = pk2n(S[8 * s2 + 4], S[8 * s2 + 5]); w.w = pk2n(S[8 * s2 + 6], S[8 * s2 + 7]);
;         pf[s2] = __builtin_bit_cast(bf16x8, w);
;     }
; #pragma unroll
;     for (int s2 = 0; s2 < 2; ++s2) {
;         o0 = __builtin_amdgcn_mfma_f32_32x32x16_bf16(vf[s2][0], pf[s2], o0, 0, 0, 0);
;         o1 = __builtin_amdgcn_mfma_f32_32x32x16_bf16(vf[s2][1], pf[s2], o1, 0, 0, 0);
;     }
.LaP_nrzbS:
	v_pk_add_f32 v[32:33], v[32:33], v[220:221] op_sel_hi:[1,0] neg_lo:[0,1] neg_hi:[0,1]
	v_pk_add_f32 v[96:97], v[96:97], v[222:223] op_sel_hi:[1,0] neg_lo:[0,1] neg_hi:[0,1]
	v_pk_add_f32 v[34:35], v[34:35], v[220:221] op_sel_hi:[1,0] neg_lo:[0,1] neg_hi:[0,1]
	v_pk_add_f32 v[98:99], v[98:99], v[222:223] op_sel_hi:[1,0] neg_lo:[0,1] neg_hi:[0,1]
	v_pk_add_f32 v[36:37], v[36:37], v[220:221] op_sel_hi:[1,0] neg_lo:[0,1] neg_hi:[0,1]
	v_pk_add_f32 v[100:101], v[100:101], v[222:223] op_sel_hi:[1,0] neg_lo:[0,1] neg_hi:[0,1]
	v_pk_add_f32 v[38:39], v[38:39], v[220:221] op_sel_hi:[1,0] neg_lo:[0,1] neg_hi:[0,1]
	v_pk_add_f32 v[102:103], v[102:103], v[222:223] op_sel_hi:[1,0] neg_lo:[0,1] neg_hi:[0,1]
	v_pk_add_f32 v[40:41], v[40:41], v[220:221] op_sel_hi:[1,0] neg_lo:[0,1] neg_hi:[0,1]
	v_pk_add_f32 v[104:105], v[104:105], v[222:223] op_sel_hi:[1,0] neg_lo:[0,1] neg_hi:[0,1]
	v_pk_add_f32 v[42:43], v[42:43], v[220:221] op_sel_hi:[1,0] neg_lo:[0,1] neg_hi:[0,1]
	v_pk_add_f32 v[106:107], v[106:107], v[222:223] op_sel_hi:[1,0] neg_lo:[0,1] neg_hi:[0,1]
	v_pk_add_f32 v[44:45], v[44:45], v[220:221] op_sel_hi:[1,0] neg_lo:[0,1] neg_hi:[0,1]
	v_pk_add_f32 v[108:109], v[108:109], v[222:223] op_sel_hi:[1,0] neg_lo:[0,1] neg_hi:[0,1]
	v_pk_add_f32 v[46:47], v[46:47], v[220:221] op_sel_hi:[1,0] neg_lo:[0,1] neg_hi:[0,1]
	v_pk_add_f32 v[110:111], v[110:111], v[222:223] op_sel_hi:[1,0] neg_lo:[0,1] neg_hi:[0,1]
	v_exp_f32_e32 v32, v32
	v_exp_f32_e32 v96, v96
	v_exp_f32_e32 v33, v33
	v_exp_f32_e32 v97, v97
	v_exp_f32_e32 v34, v34
	v_exp_f32_e32 v98, v98
	v_exp_f32_e32 v35, v35
	v_exp_f32_e32 v99, v99
	v_pk_add_f32 v[152:153], v[32:33], v[34:35]
	v_pk_add_f32 v[218:219], v[96:97], v[98:99]
	v_exp_f32_e32 v36, v36
	v_exp_f32_e32 v100, v100
	v_exp_f32_e32 v37, v37
	v_exp_f32_e32 v101, v101
	v_pk_add_f32 v[152:153], v[152:153], v[36:37]
	v_pk_add_f32 v[218:219], v[218:219], v[100:101]
	v_exp_f32_e32 v38, v38
	v_exp_f32_e32 v102, v102
	v_exp_f32_e32 v39, v39
	v_exp_f32_e32 v103, v103
	v_pk_add_f32 v[152:153], v[152:153], v[38:39]
	v_pk_add_f32 v[218:219], v[218:219], v[102:103]
	v_exp_f32_e32 v40, v40
	v_exp_f32_e32 v104, v104
	v_exp_f32_e32 v41, v41
	v_exp_f32_e32 v105, v105
	v_pk_add_f32 v[152:153], v[152:153], v[40:41]
	v_pk_add_f32 v[218:219], v[218:219], v[104:105]
	v_exp_f32_e32 v42, v42
	v_exp_f32_e32 v106, v106
	v_exp_f32_e32 v43, v43
	v_exp_f32_e32 v107, v107
	v_pk_add_f32 v[152:153], v[152:153], v[42:43]
	v_pk_add_f32 v[218:219], v[218:219], v[106:107]
	v_exp_f32_e32 v44, v44
	v_exp_f32_e32 v108, v108
	v_exp_f32_e32 v45, v45
	v_exp_f32_e32 v109, v109
	v_pk_add_f32 v[152:153], v[152:153], v[44:45]
	v_pk_add_f32 v[218:219], v[218:219], v[108:109]
	v_exp_f32_e32 v46, v46
	v_exp_f32_e32 v110, v110
	v_exp_f32_e32 v47, v47
	v_exp_f32_e32 v111, v111
	v_pk_add_f32 v[152:153], v[152:153], v[46:47]
	v_pk_add_f32 v[218:219], v[218:219], v[110:111]
	s_nop 0
	s_nop 0
	v_add_f32_e32 v152, v152, v153
	v_add_f32_e32 v218, v218, v219
	v_fma_f32 v135, v135, v140, v152
	v_fma_f32 v213, v213, v150, v218
	v_cvt_pk_bf16_f32 v32, v32, v33
	v_cvt_pk_bf16_f32 v96, v96, v97
	v_cvt_pk_bf16_f32 v33, v34, v35
	v_cvt_pk_bf16_f32 v97, v98, v99
	v_cvt_pk_bf16_f32 v34, v36, v37
	v_cvt_pk_bf16_f32 v98, v100, v101
	v_cvt_pk_bf16_f32 v35, v38, v39
	v_cvt_pk_bf16_f32 v99, v102, v103
	v_cvt_pk_bf16_f32 v36, v40, v41
	v_cvt_pk_bf16_f32 v100, v104, v105
	v_cvt_pk_bf16_f32 v37, v42, v43
	v_cvt_pk_bf16_f32 v101, v106, v107
	v_cvt_pk_bf16_f32 v38, v44, v45
	v_cvt_pk_bf16_f32 v102, v108, v109
	v_cvt_pk_bf16_f32 v39, v46, v47
	v_cvt_pk_bf16_f32 v103, v110, v111
	s_nop 0
	v_mfma_f32_32x32x16_bf16 v[16:31], v[160:163], v[32:35], v[16:31]
	v_mfma_f32_32x32x16_bf16 v[80:95], v[176:179], v[96:99], v[80:95]
	v_mfma_f32_32x32x16_bf16 v[0:15], v[164:167], v[32:35], v[0:15]
	v_mfma_f32_32x32x16_bf16 v[64:79], v[180:183], v[96:99], v[64:79]
	v_mfma_f32_32x32x16_bf16 v[16:31], v[168:171], v[36:39], v[16:31]
	v_mfma_f32_32x32x16_bf16 v[80:95], v[184:187], v[100:103], v[80:95]
	v_mfma_f32_32x32x16_bf16 v[0:15], v[172:175], v[36:39], v[0:15]
	v_mfma_f32_32x32x16_bf16 v[64:79], v[188:191], v[100:103], v[64:79]
	s_add_i32 s86, s86, 1
	s_add_i32 s2, s2, 1
	s_cmp_le_u32 s86, s87
	s_cbranch_scc1 .LaT_loopS
	s_cmp_le_u32 s2, s3
	s_cbranch_scc1 .LaT_loopS
	s_nop 15
	s_nop 7
	s_branch .LaT_epi
